# RG-LRU tiles: sqrt(max(0, 1-a*a)) -- max folded into the packed fma as its clamp modifier (60 v_max_f32 removed)
# speedup vs baseline: 1.0059x; 1.0005x over previous
.LBB0_428:
	v_mov_b32_e32 v105, v104
	v_mov_b32_e32 v106, v104
	v_mov_b32_e32 v107, v104
	v_mov_b32_e32 v97, v96
	v_mov_b32_e32 v98, v96
	s_waitcnt lgkmcnt(7)
	v_mfma_f32_16x16x32_bf16 v[114:117], v[24:27], v[108:111], v[104:107]
	v_mov_b32_e32 v99, v96
	v_add_u32_e32 v18, s34, v186
	v_lshl_add_u32 v5, v18, 1, v189
	v_mfma_f32_16x16x32_bf16 v[118:121], v[24:27], v[100:103], v[96:99]
	s_waitcnt lgkmcnt(6)
	v_mfma_f32_16x16x32_bf16 v[128:131], v[28:31], v[92:95], v[114:117]
	s_waitcnt lgkmcnt(5)
	v_mfma_f32_16x16x32_bf16 v[114:117], v[32:35], v[108:111], v[104:107]
	v_mfma_f32_16x16x32_bf16 v[204:207], v[28:31], v[88:91], v[118:121]
	s_waitcnt lgkmcnt(4)
	v_mfma_f32_16x16x32_bf16 v[218:221], v[36:39], v[92:95], v[114:117]
	ds_read_u16 v7, v5
	ds_read_u16 v17, v5 offset:1040
	ds_read_u16 v19, v5 offset:2080
	s_nop 1
	ds_read_u16 v114, v5 offset:3120
	ds_read_u16 v115, v5 offset:4160
	ds_read_u16 v125, v5 offset:5200
	ds_read_u16 v154, v5 offset:6240
	ds_read_u16 v155, v5 offset:7280
	s_waitcnt lgkmcnt(4)
	v_lshlrev_b32_e32 v123, 16, v114
	s_waitcnt lgkmcnt(3)
	v_lshlrev_b32_e32 v124, 16, v115
	v_mfma_f32_16x16x32_bf16 v[118:121], v[32:35], v[100:103], v[96:99]
	v_lshlrev_b32_e32 v126, 16, v7
	v_lshlrev_b32_e32 v127, 16, v17
	v_lshlrev_b32_e32 v122, 16, v19
	v_mfma_f32_16x16x32_bf16 v[114:117], v[40:43], v[108:111], v[104:107]
	s_waitcnt lgkmcnt(2)
	v_lshlrev_b32_e32 v125, 16, v125
	v_mfma_f32_16x16x32_bf16 v[226:229], v[40:43], v[100:103], v[96:99]
	v_mfma_f32_16x16x32_bf16 v[106:109], v[48:51], v[108:111], v[104:107]
	v_exp_f32_e32 v110, v128
	v_exp_f32_e32 v111, v129
	v_mfma_f32_16x16x32_bf16 v[96:99], v[48:51], v[100:103], v[96:99]
	v_exp_f32_e32 v102, v204
	v_exp_f32_e32 v103, v205
	v_pk_add_f32 v[100:101], v[110:111], 1.0 op_sel_hi:[1,0]
	v_mfma_f32_16x16x32_bf16 v[222:225], v[36:39], v[88:91], v[118:121]
	v_rcp_f32_e32 v100, v100
	v_rcp_f32_e32 v101, v101
	v_mfma_f32_16x16x32_bf16 v[226:229], v[44:47], v[88:91], v[226:229]
	s_waitcnt lgkmcnt(1)
	v_lshlrev_b32_e32 v120, 16, v154
	s_waitcnt lgkmcnt(0)
	v_lshlrev_b32_e32 v121, 16, v155
	ds_read_u16 v7, v5 offset:8320
	ds_read_u16 v17, v5 offset:9360
	ds_read_u16 v19, v5 offset:10400
	ds_read_u16 v154, v5 offset:11440
	ds_read_u16 v155, v5 offset:12480
	ds_read_u16 v203, v5 offset:13520
	ds_read_u16 v208, v5 offset:14560
	ds_read_u16 v5, v5 offset:15600
	v_mfma_f32_16x16x32_bf16 v[88:91], v[52:55], v[88:91], v[96:99]
	v_exp_f32_e32 v209, v229
	s_waitcnt lgkmcnt(7)
	v_lshlrev_b32_e32 v118, 16, v7
	s_waitcnt lgkmcnt(1)
	v_lshlrev_b32_e32 v104, 16, v208
	v_pk_add_f32 v[98:99], v[102:103], 1.0 op_sel_hi:[1,0]
	v_exp_f32_e32 v102, v130
	v_exp_f32_e32 v103, v131
	v_pk_mul_f32 v[96:97], v[100:101], v[6:7] op_sel_hi:[1,0]
	v_mfma_f32_16x16x32_bf16 v[230:233], v[44:47], v[92:95], v[114:117]
	v_exp_f32_e32 v96, v96
	v_pk_add_f32 v[102:103], v[102:103], 1.0 op_sel_hi:[1,0]
	v_exp_f32_e32 v97, v97
	v_rcp_f32_e32 v102, v102
	v_rcp_f32_e32 v103, v103
	s_waitcnt lgkmcnt(0)
	v_lshlrev_b32_e32 v105, 16, v5
	v_pk_fma_f32 v[100:101], v[96:97], v[96:97], 1.0 op_sel_hi:[1,1,0] neg_lo:[1,0,0] neg_hi:[1,0,0] clamp
	v_mfma_f32_16x16x32_bf16 v[92:95], v[52:55], v[92:95], v[106:109]
	v_mul_f32_e64 v102, v102, v6
	v_mul_f32_e64 v103, v103, v6
	v_exp_f32_e32 v110, v102
	v_exp_f32_e32 v111, v103
	v_exp_f32_e32 v102, v218
	v_exp_f32_e32 v103, v219
	v_exp_f32_e32 v108, v222
	v_exp_f32_e32 v109, v223
	v_rcp_f32_e32 v98, v98
	v_rcp_f32_e32 v99, v99
	v_sqrt_f32_e32 v100, v100
	v_sqrt_f32_e32 v101, v101
	v_exp_f32_e32 v106, v206
	v_exp_f32_e32 v107, v207
	v_pk_add_f32 v[102:103], v[102:103], 1.0 op_sel_hi:[1,0]
	v_pk_add_f32 v[108:109], v[108:109], 1.0 op_sel_hi:[1,0]
	v_rcp_f32_e32 v102, v102
	v_rcp_f32_e32 v103, v103
	v_pk_mul_f32 v[98:99], v[98:99], v[126:127]
	v_rcp_f32_e32 v108, v108
	v_rcp_f32_e32 v109, v109
	v_pk_mul_f32 v[98:99], v[98:99], v[100:101]
	v_pk_add_f32 v[100:101], v[106:107], 1.0 op_sel_hi:[1,0]
	v_pk_fma_f32 v[106:107], v[110:111], v[110:111], 1.0 op_sel_hi:[1,1,0] neg_lo:[1,0,0] neg_hi:[1,0,0] clamp
	v_rcp_f32_e32 v100, v100
	v_rcp_f32_e32 v101, v101
	v_sqrt_f32_e32 v106, v106
	v_pk_mul_f32 v[102:103], v[102:103], v[6:7] op_sel_hi:[1,0]
	v_sqrt_f32_e32 v107, v107
	v_exp_f32_e32 v128, v102
	v_exp_f32_e32 v129, v103
	v_pk_mul_f32 v[102:103], v[108:109], v[124:125]
	v_exp_f32_e32 v108, v220
	v_exp_f32_e32 v109, v221
	v_pk_mul_f32 v[100:101], v[100:101], v[122:123]
	v_exp_f32_e32 v204, v230
	v_pk_mul_f32 v[100:101], v[100:101], v[106:107]
	v_pk_fma_f32 v[106:107], v[128:129], v[128:129], 1.0 op_sel_hi:[1,1,0] neg_lo:[1,0,0] neg_hi:[1,0,0] clamp
	v_pk_add_f32 v[108:109], v[108:109], 1.0 op_sel_hi:[1,0]
	v_exp_f32_e32 v205, v231
	v_rcp_f32_e32 v108, v108
	v_rcp_f32_e32 v109, v109
	v_sqrt_f32_e32 v106, v106
	v_sqrt_f32_e32 v107, v107
	v_pk_add_f32 v[204:205], v[204:205], 1.0 op_sel_hi:[1,0]
	v_pk_mul_f32 v[108:109], v[108:109], v[6:7] op_sel_hi:[1,0]
	v_rcp_f32_e32 v204, v204
	v_rcp_f32_e32 v205, v205
	v_exp_f32_e32 v130, v108
	v_exp_f32_e32 v131, v109
	v_pk_mul_f32 v[102:103], v[102:103], v[106:107]
	v_exp_f32_e32 v106, v224
	v_exp_f32_e32 v107, v225
	v_pk_mul_f32 v[204:205], v[6:7], v[204:205] op_sel_hi:[0,1]
	v_pk_fma_f32 v[108:109], v[130:131], v[130:131], 1.0 op_sel_hi:[1,1,0] neg_lo:[1,0,0] neg_hi:[1,0,0] clamp
	v_exp_f32_e32 v218, v204
	v_exp_f32_e32 v219, v205
	v_exp_f32_e32 v204, v232
	v_exp_f32_e32 v205, v233
	v_pk_add_f32 v[106:107], v[106:107], 1.0 op_sel_hi:[1,0]
	v_rcp_f32_e32 v106, v106
	v_rcp_f32_e32 v107, v107
	v_sqrt_f32_e32 v108, v108
	v_sqrt_f32_e32 v109, v109
	v_exp_f32_e32 v206, v226
	v_exp_f32_e32 v207, v227
	v_pk_add_f32 v[204:205], v[204:205], 1.0 op_sel_hi:[1,0]
	v_pk_mul_f32 v[106:107], v[106:107], v[120:121]
	v_rcp_f32_e32 v204, v204
	v_rcp_f32_e32 v205, v205
	v_pk_mul_f32 v[106:107], v[106:107], v[108:109]
	v_pk_add_f32 v[108:109], v[206:207], 1.0 op_sel_hi:[1,0]
	v_pk_fma_f32 v[206:207], v[218:219], v[218:219], 1.0 op_sel_hi:[1,1,0] neg_lo:[1,0,0] neg_hi:[1,0,0] clamp
	v_exp_f32_e32 v208, v228
	v_rcp_f32_e32 v108, v108
	v_rcp_f32_e32 v109, v109
	v_sqrt_f32_e32 v206, v206
	v_pk_mul_f32 v[204:205], v[6:7], v[204:205] op_sel_hi:[0,1]
	v_sqrt_f32_e32 v207, v207
	v_exp_f32_e32 v220, v204
	v_exp_f32_e32 v221, v205
	v_lshlrev_b32_e32 v119, 16, v17
	v_pk_add_f32 v[208:209], v[208:209], 1.0 op_sel_hi:[1,0]
	v_exp_f32_e32 v92, v92
	v_exp_f32_e32 v93, v93
	v_rcp_f32_e32 v208, v208
	v_rcp_f32_e32 v209, v209
	v_pk_mul_f32 v[108:109], v[108:109], v[118:119]
	v_exp_f32_e32 v94, v94
	v_pk_mul_f32 v[108:109], v[108:109], v[206:207]
	v_pk_fma_f32 v[206:207], v[220:221], v[220:221], 1.0 op_sel_hi:[1,1,0] neg_lo:[1,0,0] neg_hi:[1,0,0] clamp
	v_exp_f32_e32 v95, v95
	v_lshlrev_b32_e32 v116, 16, v19
	v_lshlrev_b32_e32 v117, 16, v154
	v_sqrt_f32_e32 v206, v206
	v_pk_add_f32 v[92:93], v[92:93], 1.0 op_sel_hi:[1,0]
	v_pk_mul_f32 v[204:205], v[208:209], v[116:117]
	v_sqrt_f32_e32 v207, v207
	v_rcp_f32_e32 v208, v92
	v_rcp_f32_e32 v209, v93
	v_pk_add_f32 v[94:95], v[94:95], 1.0 op_sel_hi:[1,0]
	v_pk_mul_f32 v[92:93], v[204:205], v[206:207]
	v_rcp_f32_e32 v94, v94
	v_rcp_f32_e32 v95, v95
	v_pk_mul_f32 v[204:205], v[6:7], v[208:209] op_sel_hi:[0,1]
	v_exp_f32_e32 v222, v204
	v_exp_f32_e32 v223, v205
	v_exp_f32_e32 v88, v88
	v_exp_f32_e32 v89, v89
	v_pk_mul_f32 v[6:7], v[6:7], v[94:95] op_sel_hi:[0,1]
	v_exp_f32_e32 v6, v6
	v_exp_f32_e32 v7, v7
	v_exp_f32_e32 v90, v90
	v_exp_f32_e32 v91, v91
	v_pk_fma_f32 v[204:205], v[222:223], v[222:223], 1.0 op_sel_hi:[1,1,0] neg_lo:[1,0,0] neg_hi:[1,0,0] clamp
	v_pk_add_f32 v[88:89], v[88:89], 1.0 op_sel_hi:[1,0]
	v_rcp_f32_e32 v88, v88
	v_rcp_f32_e32 v89, v89
	v_sqrt_f32_e32 v204, v204
	v_pk_fma_f32 v[94:95], v[6:7], v[6:7], 1.0 op_sel_hi:[1,1,0] neg_lo:[1,0,0] neg_hi:[1,0,0] clamp
	v_sqrt_f32_e32 v205, v205
	v_pk_add_f32 v[90:91], v[90:91], 1.0 op_sel_hi:[1,0]
	v_rcp_f32_e32 v90, v90
	v_rcp_f32_e32 v91, v91
	v_sqrt_f32_e32 v206, v94
	v_fma_f32 v98, 0, v96, v98
	v_lshlrev_b32_e32 v114, 16, v155
	v_lshlrev_b32_e32 v115, 16, v203
	v_sqrt_f32_e32 v207, v95
	v_fmac_f32_e32 v99, v97, v98
	v_mul_f32_e32 v97, v96, v97
	v_pk_mul_f32 v[88:89], v[88:89], v[114:115]
	v_mul_f32_e32 v203, v110, v97
	v_fma_f32 v100, v110, v99, v100
	v_pk_mul_f32 v[94:95], v[88:89], v[204:205]
	v_fmac_f32_e32 v101, v111, v100
	v_mul_f32_e32 v204, v111, v203
	v_pk_mul_f32 v[88:89], v[90:91], v[104:105]
	v_mul_f32_e32 v205, v128, v204
	v_fma_f32 v102, v128, v101, v102
	v_pk_mul_f32 v[88:89], v[88:89], v[206:207]
	v_fmac_f32_e32 v103, v129, v102
	v_mul_f32_e32 v207, v129, v205
	v_mul_f32_e32 v208, v130, v207
	v_fma_f32 v106, v130, v103, v106
	v_fmac_f32_e32 v107, v131, v106
	v_mul_f32_e32 v212, v131, v208
	v_mul_f32_e32 v206, v218, v212
	v_fma_f32 v108, v218, v107, v108
	v_fmac_f32_e32 v109, v219, v108
	v_mul_f32_e32 v209, v219, v206
	v_mul_f32_e32 v211, v220, v209
	v_fma_f32 v92, v220, v109, v92
	v_fmac_f32_e32 v93, v221, v92
	v_mul_f32_e32 v213, v221, v211
	v_mul_f32_e32 v217, v222, v213
	v_fma_f32 v94, v222, v93, v94
	v_fmac_f32_e32 v95, v223, v94
	v_mul_f32_e32 v218, v223, v217
	v_mul_f32_e32 v219, v6, v218
	v_fma_f32 v88, v6, v95, v88
	v_fmac_f32_e32 v89, v7, v88
	v_mul_f32_e32 v90, v7, v219
	ds_bpermute_b32 v110, v182, v90
	ds_bpermute_b32 v5, v182, v89
	ds_bpermute_b32 v111, v190, v90
	ds_bpermute_b32 v17, v190, v89
	ds_bpermute_b32 v130, v191, v90
	ds_bpermute_b32 v91, v191, v89
	ds_bpermute_b32 v131, v192, v90
	ds_bpermute_b32 v7, v192, v89
	v_ashrrev_i32_e32 v19, 31, v18
	v_lshl_add_u64 v[128:129], v[18:19], 3, s[28:29]
	s_and_saveexec_b64 s[34:35], s[40:41]
	s_cbranch_execz .LBB0_430
	s_waitcnt lgkmcnt(6)
	v_fmac_f32_e32 v5, 0, v110
	s_waitcnt lgkmcnt(5)
	v_mul_f32_e32 v6, v110, v111
	s_waitcnt lgkmcnt(4)
	v_fmac_f32_e32 v17, v5, v111
	s_waitcnt lgkmcnt(3)
	v_mul_f32_e32 v6, v6, v130
	s_waitcnt lgkmcnt(2)
	v_fmac_f32_e32 v91, v17, v130
	s_waitcnt lgkmcnt(1)
	v_mul_f32_e32 v6, v6, v131
	s_waitcnt lgkmcnt(0)
	v_fmac_f32_e32 v7, v91, v131
	global_store_dwordx2 v[128:129], v[6:7], off sc1
.LBB0_430:
	s_or_b64 exec, exec, s[34:35]
	s_waitcnt lgkmcnt(4)
	v_mov_b32_e32 v17, v16
	v_mov_b32_e32 v18, v16
	v_mov_b32_e32 v19, v16
	v_mov_b32_e32 v5, v4
	v_mov_b32_e32 v6, v4
	v_mfma_f32_16x16x32_bf16 v[220:223], v[24:27], v[20:23], v[16:19]
	s_waitcnt lgkmcnt(0)
	v_mov_b32_e32 v7, v4
	v_mfma_f32_16x16x32_bf16 v[220:223], v[28:31], v[12:15], v[220:223]
	s_nop 0
	v_mfma_f32_16x16x32_bf16 v[224:227], v[24:27], v[8:11], v[4:7]
	v_mfma_f32_16x16x32_bf16 v[224:227], v[28:31], v[0:3], v[224:227]
	s_nop 4
	v_exp_f32_e32 v110, v220
	v_exp_f32_e32 v111, v221
	v_mfma_f32_16x16x32_bf16 v[228:231], v[32:35], v[20:23], v[16:19]
	v_add_f32_e64 v110, v110, 1.0
	v_add_f32_e64 v111, v111, 1.0
	v_exp_f32_e32 v130, v224
	v_exp_f32_e32 v131, v225
	v_rcp_f32_e32 v110, v110
	v_rcp_f32_e32 v111, v111
	v_mfma_f32_16x16x32_bf16 v[228:231], v[36:39], v[12:15], v[228:231]
	v_add_f32_e64 v130, v130, 1.0
	v_add_f32_e64 v131, v131, 1.0
	v_exp_f32_e32 v224, v222
	v_pk_mul_f32 v[110:111], v[110:111], v[148:149] op_sel_hi:[1,0]
	v_rcp_f32_e32 v220, v130
	v_rcp_f32_e32 v221, v131
	v_exp_f32_e32 v130, v110
	v_exp_f32_e32 v131, v111
	v_exp_f32_e32 v225, v223
	v_pk_mul_f32 v[110:111], v[220:221], v[126:127]
	v_mfma_f32_16x16x32_bf16 v[220:223], v[40:43], v[20:23], v[16:19]
	v_fma_f32 v126, -v130, v130, 1.0
	v_fma_f32 v127, -v131, v131, 1.0
	v_pk_add_f32 v[224:225], v[224:225], 1.0 op_sel_hi:[1,0]
	v_max_f32_e32 v91, 0, v126
	v_sqrt_f32_e32 v126, v91
	v_max_f32_e32 v91, 0, v127
	v_mfma_f32_16x16x32_bf16 v[16:19], v[48:51], v[20:23], v[16:19]
	v_exp_f32_e32 v22, v228
	v_exp_f32_e32 v23, v229
	v_sqrt_f32_e32 v127, v91
	v_mfma_f32_16x16x32_bf16 v[232:235], v[32:35], v[8:11], v[4:7]
	v_exp_f32_e32 v226, v226
	v_exp_f32_e32 v227, v227
	v_rcp_f32_e32 v224, v224
	v_mfma_f32_16x16x32_bf16 v[236:239], v[40:43], v[8:11], v[4:7]
	v_rcp_f32_e32 v225, v225
	v_pk_mul_f32 v[110:111], v[110:111], v[126:127]
	v_pk_add_f32 v[240:241], v[226:227], 1.0 op_sel_hi:[1,0]
	v_mfma_f32_16x16x32_bf16 v[4:7], v[48:51], v[8:11], v[4:7]
	v_mul_f32_e64 v126, v224, v148
	v_mul_f32_e64 v127, v225, v148
	v_exp_f32_e32 v126, v126
	v_mfma_f32_16x16x32_bf16 v[220:223], v[44:47], v[12:15], v[220:223]
	v_exp_f32_e32 v127, v127
	s_nop 0
	v_pk_fma_f32 v[20:21], v[126:127], v[126:127], 1.0 op_sel_hi:[1,1,0] neg_lo:[1,0,0] neg_hi:[1,0,0] clamp
	v_mfma_f32_16x16x32_bf16 v[10:13], v[52:55], v[12:15], v[16:19]
	v_sqrt_f32_e32 v8, v20
	s_nop 0
	v_pk_add_f32 v[18:19], v[22:23], 1.0 op_sel_hi:[1,0]
	v_mfma_f32_16x16x32_bf16 v[232:235], v[36:39], v[0:3], v[232:235]
	s_nop 2
	v_exp_f32_e32 v10, v10
	v_exp_f32_e32 v11, v11
	v_exp_f32_e32 v12, v12
	v_mfma_f32_16x16x32_bf16 v[224:227], v[44:47], v[0:3], v[236:239]
	v_exp_f32_e32 v13, v13
	v_exp_f32_e32 v22, v232
	v_exp_f32_e32 v23, v233
	v_mfma_f32_16x16x32_bf16 v[14:17], v[52:55], v[0:3], v[4:7]
	v_rcp_f32_e32 v0, v18
	v_rcp_f32_e32 v1, v19
	v_rcp_f32_e32 v236, v240
	v_rcp_f32_e32 v237, v241
	v_pk_mul_f32 v[0:1], v[0:1], v[148:149] op_sel_hi:[1,0]
	v_sqrt_f32_e32 v9, v21
	v_exp_f32_e32 v228, v0
	v_exp_f32_e32 v229, v1
	v_pk_add_f32 v[2:3], v[22:23], 1.0 op_sel_hi:[1,0]
	v_exp_f32_e32 v6, v230
	v_rcp_f32_e32 v2, v2
	v_pk_fma_f32 v[4:5], v[228:229], v[228:229], 1.0 op_sel_hi:[1,1,0] neg_lo:[1,0,0] neg_hi:[1,0,0] clamp
	v_rcp_f32_e32 v3, v3
	v_sqrt_f32_e32 v4, v4
	v_sqrt_f32_e32 v5, v5
	v_exp_f32_e32 v7, v231
	v_pk_mul_f32 v[0:1], v[236:237], v[122:123]
	v_pk_mul_f32 v[2:3], v[2:3], v[124:125]
	v_pk_mul_f32 v[0:1], v[0:1], v[8:9]
	v_exp_f32_e32 v8, v220
	v_exp_f32_e32 v9, v221
	v_pk_mul_f32 v[2:3], v[2:3], v[4:5]
	v_exp_f32_e32 v4, v234
	v_exp_f32_e32 v5, v235
	v_pk_add_f32 v[6:7], v[6:7], 1.0 op_sel_hi:[1,0]
	v_pk_add_f32 v[8:9], v[8:9], 1.0 op_sel_hi:[1,0]
	v_rcp_f32_e32 v6, v6
	v_rcp_f32_e32 v7, v7
	v_pk_add_f32 v[4:5], v[4:5], 1.0 op_sel_hi:[1,0]
	v_rcp_f32_e32 v8, v8
	v_rcp_f32_e32 v9, v9
	v_rcp_f32_e32 v4, v4
	v_rcp_f32_e32 v5, v5
	v_pk_mul_f32 v[6:7], v[6:7], v[148:149] op_sel_hi:[1,0]
	v_pk_mul_f32 v[8:9], v[148:149], v[8:9] op_sel_hi:[0,1]
	v_exp_f32_e32 v122, v6
	v_exp_f32_e32 v123, v7
	v_pk_mul_f32 v[4:5], v[4:5], v[120:121]
	v_exp_f32_e32 v120, v8
	v_exp_f32_e32 v121, v9
	v_exp_f32_e32 v8, v222
	v_exp_f32_e32 v9, v223
	v_pk_fma_f32 v[6:7], v[122:123], v[122:123], 1.0 op_sel_hi:[1,1,0] neg_lo:[1,0,0] neg_hi:[1,0,0] clamp
	v_exp_f32_e32 v18, v224
	v_sqrt_f32_e32 v6, v6
	v_sqrt_f32_e32 v7, v7
	v_exp_f32_e32 v19, v225
	v_pk_add_f32 v[8:9], v[8:9], 1.0 op_sel_hi:[1,0]
	v_exp_f32_e32 v20, v226
	v_rcp_f32_e32 v8, v8
	v_rcp_f32_e32 v9, v9
	v_exp_f32_e32 v21, v227
	v_pk_mul_f32 v[4:5], v[4:5], v[6:7]
	v_pk_add_f32 v[6:7], v[18:19], 1.0 op_sel_hi:[1,0]
	v_pk_fma_f32 v[18:19], v[120:121], v[120:121], 1.0 op_sel_hi:[1,1,0] neg_lo:[1,0,0] neg_hi:[1,0,0] clamp
	v_rcp_f32_e32 v6, v6
	v_rcp_f32_e32 v7, v7
	v_pk_mul_f32 v[8:9], v[148:149], v[8:9] op_sel_hi:[0,1]
	v_sqrt_f32_e32 v18, v18
	v_sqrt_f32_e32 v19, v19
	v_exp_f32_e32 v22, v8
	v_exp_f32_e32 v23, v9
	v_pk_add_f32 v[20:21], v[20:21], 1.0 op_sel_hi:[1,0]
	v_pk_mul_f32 v[6:7], v[6:7], v[118:119]
	v_rcp_f32_e32 v20, v20
	v_rcp_f32_e32 v21, v21
	v_pk_mul_f32 v[6:7], v[6:7], v[18:19]
	v_pk_fma_f32 v[18:19], v[22:23], v[22:23], 1.0 op_sel_hi:[1,1,0] neg_lo:[1,0,0] neg_hi:[1,0,0] clamp
	v_pk_add_f32 v[10:11], v[10:11], 1.0 op_sel_hi:[1,0]
	v_pk_mul_f32 v[8:9], v[20:21], v[116:117]
	v_sqrt_f32_e32 v18, v18
	v_sqrt_f32_e32 v19, v19
	v_rcp_f32_e32 v20, v10
	v_rcp_f32_e32 v21, v11
	v_pk_mul_f32 v[10:11], v[8:9], v[18:19]
	v_exp_f32_e32 v8, v14
	v_exp_f32_e32 v9, v15
	v_pk_mul_f32 v[14:15], v[148:149], v[20:21] op_sel_hi:[0,1]
	v_exp_f32_e32 v20, v14
	v_exp_f32_e32 v21, v15
	v_pk_add_f32 v[8:9], v[8:9], 1.0 op_sel_hi:[1,0]
	s_nop 0
	v_rcp_f32_e32 v14, v8
	v_rcp_f32_e32 v15, v9
	v_pk_fma_f32 v[8:9], v[20:21], v[20:21], 1.0 op_sel_hi:[1,1,0] neg_lo:[1,0,0] neg_hi:[1,0,0] clamp
	v_pk_mul_f32 v[14:15], v[14:15], v[114:115]
	v_sqrt_f32_e32 v18, v8
	v_max_f32_e32 v19, 0, v9
	v_pk_add_f32 v[8:9], v[12:13], 1.0 op_sel_hi:[1,0]
	v_exp_f32_e32 v12, v16
	v_rcp_f32_e32 v8, v8
	v_rcp_f32_e32 v9, v9
	v_exp_f32_e32 v13, v17
	v_sqrt_f32_e32 v19, v19
	v_pk_mul_f32 v[8:9], v[148:149], v[8:9] op_sel_hi:[0,1]
	v_exp_f32_e32 v8, v8
	v_exp_f32_e32 v9, v9
	v_pk_add_f32 v[12:13], v[12:13], 1.0 op_sel_hi:[1,0]
	v_pk_mul_f32 v[14:15], v[14:15], v[18:19]
	v_rcp_f32_e32 v12, v12
	v_pk_fma_f32 v[16:17], v[8:9], v[8:9], 1.0 op_sel_hi:[1,1,0] neg_lo:[1,0,0] neg_hi:[1,0,0] clamp
	v_rcp_f32_e32 v13, v13
	v_sqrt_f32_e32 v16, v16
	v_sqrt_f32_e32 v17, v17
	v_pk_mul_f32 v[12:13], v[12:13], v[104:105]
	s_nop 0
	v_pk_mul_f32 v[12:13], v[12:13], v[16:17]
	s_nop 0
	v_fma_f32 v13, 0, v9, v13
	v_fmac_f32_e32 v12, v8, v13
	v_mul_f32_e32 v8, v9, v8
	v_mul_f32_e32 v18, v21, v8
	v_fma_f32 v15, v21, v12, v15
	v_fmac_f32_e32 v14, v20, v15
	v_mul_f32_e32 v19, v20, v18
	v_mul_f32_e32 v20, v23, v19
	v_fma_f32 v11, v23, v14, v11
	v_fmac_f32_e32 v10, v22, v11
	v_mul_f32_e32 v21, v22, v20
	v_mul_f32_e32 v22, v121, v21
	v_fma_f32 v7, v121, v10, v7
	v_fmac_f32_e32 v6, v120, v7
	v_mul_f32_e32 v23, v120, v22
	v_mul_f32_e32 v104, v123, v23
	v_fma_f32 v5, v123, v6, v5
	v_fmac_f32_e32 v4, v122, v5
	v_mul_f32_e32 v105, v122, v104
	v_mul_f32_e32 v114, v229, v105
	v_fma_f32 v3, v229, v4, v3
	v_fmac_f32_e32 v2, v228, v3
	v_mul_f32_e32 v115, v228, v114
	v_mul_f32_e32 v116, v127, v115
	v_fma_f32 v1, v127, v2, v1
	v_fmac_f32_e32 v0, v126, v1
	v_mul_f32_e32 v117, v126, v116
	v_mul_f32_e32 v118, v131, v117
	v_fma_f32 v111, v131, v0, v111
	v_fmac_f32_e32 v110, v130, v111
	v_mul_f32_e32 v91, v130, v118
	ds_bpermute_b32 v122, v192, v91
	ds_bpermute_b32 v119, v192, v110
	ds_bpermute_b32 v123, v191, v91
	ds_bpermute_b32 v120, v191, v110
	ds_bpermute_b32 v124, v190, v91
	ds_bpermute_b32 v121, v190, v110
	ds_bpermute_b32 v125, v182, v91
	ds_bpermute_b32 v17, v182, v110
	s_and_saveexec_b64 s[34:35], s[40:41]
	s_cbranch_execz .LBB0_425
	s_waitcnt lgkmcnt(6)
	v_fmac_f32_e32 v119, 0, v122
	s_waitcnt lgkmcnt(5)
	v_mul_f32_e32 v16, v122, v123
	s_waitcnt lgkmcnt(4)
	v_fmac_f32_e32 v120, v119, v123
	s_waitcnt lgkmcnt(3)
	v_mul_f32_e32 v16, v16, v124
	s_waitcnt lgkmcnt(2)
	v_fmac_f32_e32 v121, v120, v124
	v_add_co_u32_e32 v120, vcc, 0x1000, v128
	s_waitcnt lgkmcnt(1)
	v_mul_f32_e32 v16, v16, v125
	s_waitcnt lgkmcnt(0)
	v_fmac_f32_e32 v17, v121, v125
	v_addc_co_u32_e32 v121, vcc, 0, v129, vcc
	global_store_dwordx2 v[120:121], v[16:17], off sc1
	s_branch .LBB0_425

.LBB0_507:
	s_or_b32 s48, s48, s36
	s_lshl_b32 s34, s48, 4
	v_or_b32_e32 v54, s34, v109
	v_or_b32_e32 v0, s34, v108
	v_add_u32_e32 v6, v54, v79
	v_lshlrev_b32_e32 v148, 7, v0
	v_ashrrev_i32_e32 v7, 31, v6
	v_lshl_add_u64 v[4:5], v[62:63], 0, v[148:149]
	v_lshl_add_u64 v[6:7], v[6:7], 2, s[4:5]
	global_load_dwordx4 v[0:3], v[4:5], off
	global_load_dword v58, v[6:7], off
	v_add_u32_e32 v6, s37, v54
	v_ashrrev_i32_e32 v7, 31, v6
	v_lshl_add_u64 v[6:7], v[6:7], 2, s[4:5]
	global_load_dword v72, v[6:7], off
	v_lshl_add_u64 v[6:7], v[64:65], 0, v[148:149]
	global_load_dwordx4 v[80:83], v[6:7], off
	global_load_dwordx4 v[84:87], v[4:5], off offset:64
	global_load_dwordx4 v[116:119], v[6:7], off offset:64
	v_add_u32_e32 v24, s42, v54
	v_ashrrev_i32_e32 v25, 31, v24
	v_lshl_add_u64 v[24:25], v[24:25], 2, s[22:23]
	ds_read_b128 v[28:31], v115
	ds_read_b128 v[20:23], v115 offset:64
	ds_read_b128 v[16:19], v115 offset:4160
	ds_read_b128 v[12:15], v115 offset:4224
	ds_read_b128 v[8:11], v115 offset:8320
	ds_read_b128 v[4:7], v115 offset:8384
	v_lshl_add_u64 v[44:45], v[66:67], 0, v[148:149]
	global_load_dword v94, v[24:25], off
	s_nop 0
	global_load_dwordx4 v[24:27], v[44:45], off
	ds_read_b128 v[36:39], v115 offset:12480
	ds_read_b128 v[32:35], v115 offset:12544
	v_add_u32_e32 v52, s43, v54
	v_add_u32_e32 v56, s46, v54
	v_ashrrev_i32_e32 v53, 31, v52
	v_subrev_u32_e32 v92, s47, v52
	v_lshl_add_u32 v46, v54, 1, v110
	v_lshl_add_u64 v[76:77], v[68:69], 0, v[148:149]
	v_ashrrev_i32_e32 v57, 31, v56
	v_lshl_add_u64 v[52:53], v[52:53], 2, s[4:5]
	v_ashrrev_i32_e32 v93, 31, v92
	ds_read_u16 v55, v46
	ds_read_u16 v95, v46 offset:1040
	ds_read_u16 v102, v46 offset:2080
	ds_read_u16 v103, v46 offset:3120
	ds_read_u16 v106, v46 offset:4160
	ds_read_u16 v107, v46 offset:5200
	ds_read_u16 v144, v46 offset:6240
	ds_read_u16 v145, v46 offset:7280
	ds_read_u16 v147, v46 offset:8320
	ds_read_u16 v148, v46 offset:9360
	ds_read_u16 v154, v46 offset:10400
	ds_read_u16 v155, v46 offset:11440
	ds_read_u16 v156, v46 offset:12480
	ds_read_u16 v157, v46 offset:13520
	ds_read_u16 v158, v46 offset:14560
	ds_read_u16 v159, v46 offset:15600
	v_lshl_add_u64 v[100:101], v[56:57], 2, s[4:5]
	v_lshl_add_u64 v[92:93], v[92:93], 2, s[22:23]
	s_waitcnt lgkmcnt(14)
	v_lshlrev_b32_e32 v104, 16, v55
	v_lshlrev_b32_e32 v105, 16, v95
	s_waitcnt lgkmcnt(13)
	v_lshlrev_b32_e32 v102, 16, v102
	s_waitcnt lgkmcnt(12)
	v_lshlrev_b32_e32 v103, 16, v103
	v_ashrrev_i32_e32 v55, 31, v54
	s_waitcnt vmcnt(6)
	v_mov_b32_e32 v59, v58
	v_mov_b32_e32 v60, v58
	v_mov_b32_e32 v61, v58
	s_waitcnt vmcnt(5)
	v_mov_b32_e32 v73, v72
	v_mfma_f32_16x16x32_bf16 v[40:43], v[28:31], v[0:3], v[58:61]
	v_mov_b32_e32 v74, v72
	v_mov_b32_e32 v75, v72
	s_waitcnt vmcnt(3)
	v_mfma_f32_16x16x32_bf16 v[128:131], v[20:23], v[84:87], v[40:43]
	s_nop 3
	global_load_dwordx4 v[40:43], v[76:77], off
	s_nop 0
	global_load_dwordx4 v[44:47], v[44:45], off offset:64
	v_mfma_f32_16x16x32_bf16 v[48:51], v[28:31], v[80:83], v[72:75]
	v_mfma_f32_16x16x32_bf16 v[88:91], v[16:19], v[0:3], v[58:61]
	v_mfma_f32_16x16x32_bf16 v[120:123], v[8:11], v[0:3], v[58:61]
	s_waitcnt vmcnt(4)
	v_mfma_f32_16x16x32_bf16 v[132:135], v[20:23], v[116:119], v[48:51]
	s_nop 3
	global_load_dwordx4 v[48:51], v[76:77], off offset:64
	global_load_dword v56, v[52:53], off
	s_nop 0
	global_load_dword v52, v[100:101], off
	global_load_dword v78, v[92:93], off
	v_exp_f32_e32 v76, v128
	v_exp_f32_e32 v77, v129
	v_mfma_f32_16x16x32_bf16 v[0:3], v[36:39], v[0:3], v[58:61]
	s_waitcnt lgkmcnt(11)
	v_lshlrev_b32_e32 v100, 16, v106
	s_waitcnt lgkmcnt(10)
	v_lshlrev_b32_e32 v101, 16, v107
	s_waitcnt lgkmcnt(5)
	v_lshlrev_b32_e32 v92, 16, v154
	v_mfma_f32_16x16x32_bf16 v[96:99], v[16:19], v[80:83], v[72:75]
	s_waitcnt lgkmcnt(4)
	v_lshlrev_b32_e32 v93, 16, v155
	v_mfma_f32_16x16x32_bf16 v[124:127], v[8:11], v[80:83], v[72:75]
	v_mfma_f32_16x16x32_bf16 v[72:75], v[36:39], v[80:83], v[72:75]
	v_exp_f32_e32 v80, v130
	v_exp_f32_e32 v81, v131
	s_waitcnt lgkmcnt(1)
	v_lshlrev_b32_e32 v82, 16, v158
	v_mfma_f32_16x16x32_bf16 v[58:61], v[32:35], v[84:87], v[0:3]
	s_waitcnt lgkmcnt(0)
	v_lshlrev_b32_e32 v83, 16, v159
	v_pk_add_f32 v[80:81], v[80:81], 1.0 op_sel_hi:[1,0]
	v_pk_add_f32 v[0:1], v[76:77], 1.0 op_sel_hi:[1,0]
	v_rcp_f32_e32 v80, v80
	v_rcp_f32_e32 v76, v0
	v_rcp_f32_e32 v77, v1
	v_mfma_f32_16x16x32_bf16 v[0:3], v[32:35], v[116:119], v[72:75]
	v_rcp_f32_e32 v81, v81
	v_exp_f32_e32 v58, v58
	v_exp_f32_e32 v59, v59
	s_waitcnt vmcnt(7)
	v_pk_mul_f32 v[72:73], v[76:77], v[94:95] op_sel_hi:[1,0]
	v_mfma_f32_16x16x32_bf16 v[136:139], v[12:15], v[84:87], v[88:91]
	v_exp_f32_e32 v72, v72
	v_exp_f32_e32 v73, v73
	v_exp_f32_e32 v74, v132
	v_mfma_f32_16x16x32_bf16 v[140:143], v[12:15], v[116:119], v[96:99]
	v_exp_f32_e32 v75, v133
	v_pk_mul_f32 v[80:81], v[80:81], v[94:95] op_sel_hi:[1,0]
	v_pk_fma_f32 v[76:77], v[72:73], v[72:73], 1.0 op_sel_hi:[1,1,0] neg_lo:[1,0,0] neg_hi:[1,0,0] clamp
	v_exp_f32_e32 v106, v80
	v_exp_f32_e32 v107, v81
	v_exp_f32_e32 v80, v136
	v_exp_f32_e32 v81, v137
	v_mfma_f32_16x16x32_bf16 v[120:123], v[4:7], v[84:87], v[120:123]
	v_add_f32_e64 v74, v74, 1.0
	v_add_f32_e64 v75, v75, 1.0
	v_exp_f32_e32 v86, v140
	v_exp_f32_e32 v87, v141
	v_rcp_f32_e32 v74, v74
	v_rcp_f32_e32 v75, v75
	v_sqrt_f32_e32 v76, v76
	v_sqrt_f32_e32 v77, v77
	v_exp_f32_e32 v84, v134
	v_exp_f32_e32 v85, v135
	v_pk_add_f32 v[80:81], v[80:81], 1.0 op_sel_hi:[1,0]
	v_pk_add_f32 v[86:87], v[86:87], 1.0 op_sel_hi:[1,0]
	v_rcp_f32_e32 v80, v80
	v_rcp_f32_e32 v81, v81
	v_pk_mul_f32 v[74:75], v[74:75], v[104:105]
	v_rcp_f32_e32 v86, v86
	v_rcp_f32_e32 v87, v87
	v_pk_mul_f32 v[74:75], v[74:75], v[76:77]
	v_pk_add_f32 v[76:77], v[84:85], 1.0 op_sel_hi:[1,0]
	v_pk_fma_f32 v[84:85], v[106:107], v[106:107], 1.0 op_sel_hi:[1,1,0] neg_lo:[1,0,0] neg_hi:[1,0,0] clamp
	v_rcp_f32_e32 v76, v76
	v_rcp_f32_e32 v77, v77
	v_sqrt_f32_e32 v84, v84
	v_pk_mul_f32 v[80:81], v[80:81], v[94:95] op_sel_hi:[1,0]
	v_mfma_f32_16x16x32_bf16 v[124:127], v[4:7], v[116:119], v[124:127]
	v_sqrt_f32_e32 v85, v85
	v_exp_f32_e32 v118, v80
	v_exp_f32_e32 v119, v81
	v_pk_mul_f32 v[80:81], v[86:87], v[100:101]
	v_exp_f32_e32 v86, v138
	v_exp_f32_e32 v87, v139
	v_pk_mul_f32 v[76:77], v[76:77], v[102:103]
	v_exp_f32_e32 v88, v120
	v_pk_mul_f32 v[76:77], v[76:77], v[84:85]
	v_pk_fma_f32 v[84:85], v[118:119], v[118:119], 1.0 op_sel_hi:[1,1,0] neg_lo:[1,0,0] neg_hi:[1,0,0] clamp
	v_pk_add_f32 v[86:87], v[86:87], 1.0 op_sel_hi:[1,0]
	v_exp_f32_e32 v89, v121
	v_rcp_f32_e32 v86, v86
	v_rcp_f32_e32 v87, v87
	v_sqrt_f32_e32 v84, v84
	v_sqrt_f32_e32 v85, v85
	v_pk_add_f32 v[88:89], v[88:89], 1.0 op_sel_hi:[1,0]
	v_pk_mul_f32 v[86:87], v[86:87], v[94:95] op_sel_hi:[1,0]
	v_rcp_f32_e32 v88, v88
	v_rcp_f32_e32 v89, v89
	v_exp_f32_e32 v128, v86
	v_exp_f32_e32 v129, v87
	v_pk_mul_f32 v[80:81], v[80:81], v[84:85]
	v_exp_f32_e32 v84, v142
	v_exp_f32_e32 v85, v143
	v_pk_mul_f32 v[88:89], v[94:95], v[88:89] op_sel_hi:[0,1]
	v_pk_fma_f32 v[86:87], v[128:129], v[128:129], 1.0 op_sel_hi:[1,1,0] neg_lo:[1,0,0] neg_hi:[1,0,0] clamp
	v_exp_f32_e32 v120, v88
	v_exp_f32_e32 v121, v89
	v_exp_f32_e32 v88, v122
	v_exp_f32_e32 v89, v123
	v_pk_add_f32 v[84:85], v[84:85], 1.0 op_sel_hi:[1,0]
	v_rcp_f32_e32 v84, v84
	v_rcp_f32_e32 v85, v85
	v_sqrt_f32_e32 v86, v86
	v_sqrt_f32_e32 v87, v87
	v_exp_f32_e32 v116, v124
	v_exp_f32_e32 v117, v125
	v_pk_add_f32 v[88:89], v[88:89], 1.0 op_sel_hi:[1,0]
	v_lshlrev_b32_e32 v98, 16, v144
	v_lshlrev_b32_e32 v99, 16, v145
	v_rcp_f32_e32 v88, v88
	v_rcp_f32_e32 v89, v89
	v_pk_mul_f32 v[84:85], v[84:85], v[98:99]
	v_exp_f32_e32 v122, v126
	v_pk_mul_f32 v[84:85], v[84:85], v[86:87]
	v_pk_add_f32 v[86:87], v[116:117], 1.0 op_sel_hi:[1,0]
	v_pk_fma_f32 v[116:117], v[120:121], v[120:121], 1.0 op_sel_hi:[1,1,0] neg_lo:[1,0,0] neg_hi:[1,0,0] clamp
	v_rcp_f32_e32 v86, v86
	v_rcp_f32_e32 v87, v87
	v_sqrt_f32_e32 v116, v116
	v_pk_mul_f32 v[88:89], v[94:95], v[88:89] op_sel_hi:[0,1]
	v_sqrt_f32_e32 v117, v117
	v_exp_f32_e32 v124, v88
	v_exp_f32_e32 v125, v89
	v_exp_f32_e32 v123, v127
	v_pk_add_f32 v[58:59], v[58:59], 1.0 op_sel_hi:[1,0]
	v_lshlrev_b32_e32 v96, 16, v147
	v_lshlrev_b32_e32 v97, 16, v148
	v_rcp_f32_e32 v58, v58
	v_rcp_f32_e32 v59, v59
	v_exp_f32_e32 v60, v60
	v_exp_f32_e32 v61, v61
	v_pk_mul_f32 v[86:87], v[86:87], v[96:97]
	v_pk_add_f32 v[122:123], v[122:123], 1.0 op_sel_hi:[1,0]
	v_pk_mul_f32 v[86:87], v[86:87], v[116:117]
	v_pk_fma_f32 v[116:117], v[124:125], v[124:125], 1.0 op_sel_hi:[1,1,0] neg_lo:[1,0,0] neg_hi:[1,0,0] clamp
	v_rcp_f32_e32 v122, v122
	v_rcp_f32_e32 v123, v123
	v_sqrt_f32_e32 v116, v116
	v_pk_mul_f32 v[58:59], v[94:95], v[58:59] op_sel_hi:[0,1]
	v_pk_add_f32 v[60:61], v[60:61], 1.0 op_sel_hi:[1,0]
	v_sqrt_f32_e32 v117, v117
	v_exp_f32_e32 v58, v58
	v_exp_f32_e32 v59, v59
	v_rcp_f32_e32 v60, v60
	v_rcp_f32_e32 v61, v61
	v_exp_f32_e32 v0, v0
	v_exp_f32_e32 v1, v1
	v_pk_mul_f32 v[88:89], v[122:123], v[92:93]
	v_pk_mul_f32 v[60:61], v[94:95], v[60:61] op_sel_hi:[0,1]
	v_pk_mul_f32 v[88:89], v[88:89], v[116:117]
	v_pk_fma_f32 v[116:117], v[58:59], v[58:59], 1.0 op_sel_hi:[1,1,0] neg_lo:[1,0,0] neg_hi:[1,0,0] clamp
	v_pk_add_f32 v[0:1], v[0:1], 1.0 op_sel_hi:[1,0]
	v_exp_f32_e32 v94, v60
	v_exp_f32_e32 v95, v61
	v_rcp_f32_e32 v0, v0
	v_rcp_f32_e32 v1, v1
	v_sqrt_f32_e32 v116, v116
	v_exp_f32_e32 v2, v2
	v_exp_f32_e32 v3, v3
	v_sqrt_f32_e32 v117, v117
	v_lshlrev_b32_e32 v90, 16, v156
	v_lshlrev_b32_e32 v91, 16, v157
	v_pk_fma_f32 v[60:61], v[94:95], v[94:95], 1.0 op_sel_hi:[1,1,0] neg_lo:[1,0,0] neg_hi:[1,0,0] clamp
	v_fma_f32 v74, 0, v72, v74
	v_pk_add_f32 v[2:3], v[2:3], 1.0 op_sel_hi:[1,0]
	v_pk_mul_f32 v[0:1], v[0:1], v[90:91]
	v_fmac_f32_e32 v75, v73, v74
	v_mul_f32_e32 v73, v72, v73
	v_rcp_f32_e32 v2, v2
	v_rcp_f32_e32 v3, v3
	v_sqrt_f32_e32 v122, v60
	v_max_f32_e32 v53, 0, v61
	v_pk_mul_f32 v[60:61], v[0:1], v[116:117]
	v_mul_f32_e32 v116, v106, v73
	v_fma_f32 v76, v106, v75, v76
	v_sqrt_f32_e32 v123, v53
	v_fmac_f32_e32 v77, v107, v76
	v_mul_f32_e32 v106, v107, v116
	v_mul_f32_e32 v107, v118, v106
	v_fma_f32 v80, v118, v77, v80
	v_fmac_f32_e32 v81, v119, v80
	v_mul_f32_e32 v118, v119, v107
	v_pk_mul_f32 v[0:1], v[2:3], v[82:83]
	v_mul_f32_e32 v119, v128, v118
	v_fma_f32 v84, v128, v81, v84
	v_pk_mul_f32 v[0:1], v[0:1], v[122:123]
	v_fmac_f32_e32 v85, v129, v84
	v_mul_f32_e32 v122, v129, v119
	v_mul_f32_e32 v117, v120, v122
	v_fma_f32 v86, v120, v85, v86
	v_fmac_f32_e32 v87, v121, v86
	v_mul_f32_e32 v120, v121, v117
	v_mul_f32_e32 v121, v124, v120
	v_fma_f32 v88, v124, v87, v88
	v_fmac_f32_e32 v89, v125, v88
	v_mul_f32_e32 v123, v125, v121
	v_mul_f32_e32 v124, v58, v123
	v_fma_f32 v60, v58, v89, v60
	v_fmac_f32_e32 v61, v59, v60
	v_mul_f32_e32 v125, v59, v124
	v_mul_f32_e32 v126, v94, v125
	v_fma_f32 v0, v94, v61, v0
	v_fmac_f32_e32 v1, v95, v0
	v_mul_f32_e32 v2, v95, v126
	ds_bpermute_b32 v127, v111, v2
	ds_bpermute_b32 v3, v111, v1
	ds_bpermute_b32 v128, v112, v2
	ds_bpermute_b32 v53, v112, v1
	ds_bpermute_b32 v129, v113, v2
	ds_bpermute_b32 v57, v113, v1
	ds_bpermute_b32 v130, v114, v2
	ds_bpermute_b32 v59, v114, v1
	v_lshl_add_u64 v[94:95], v[54:55], 3, s[24:25]
	s_and_saveexec_b64 s[34:35], s[40:41]
	s_cbranch_execz .LBB0_509
	s_waitcnt lgkmcnt(6)
	v_fmac_f32_e32 v3, 0, v127
	s_waitcnt lgkmcnt(5)
	v_mul_f32_e32 v54, v127, v128
	s_waitcnt lgkmcnt(4)
	v_fmac_f32_e32 v53, v3, v128
	s_waitcnt lgkmcnt(3)
	v_mul_f32_e32 v54, v54, v129
	s_waitcnt lgkmcnt(2)
	v_fmac_f32_e32 v57, v53, v129
	s_waitcnt lgkmcnt(1)
	v_mul_f32_e32 v58, v54, v130
	s_waitcnt lgkmcnt(0)
	v_fmac_f32_e32 v59, v57, v130
	global_store_dwordx2 v[94:95], v[58:59], off sc1
.LBB0_509:
	s_or_b64 exec, exec, s[34:35]
	s_waitcnt vmcnt(2) lgkmcnt(2)
	v_mov_b32_e32 v57, v56
	v_mov_b32_e32 v58, v56
	s_waitcnt lgkmcnt(0)
	v_mov_b32_e32 v59, v56
	s_waitcnt vmcnt(1)
	v_mov_b32_e32 v53, v52
	v_mov_b32_e32 v54, v52
	v_mov_b32_e32 v55, v52
	v_mfma_f32_16x16x32_bf16 v[128:131], v[28:31], v[24:27], v[56:59]
	s_nop 0
	v_mfma_f32_16x16x32_bf16 v[28:31], v[28:31], v[40:43], v[52:55]
	v_mfma_f32_16x16x32_bf16 v[128:131], v[20:23], v[44:47], v[128:131]
	v_mfma_f32_16x16x32_bf16 v[132:135], v[20:23], v[48:51], v[28:31]
	v_mfma_f32_16x16x32_bf16 v[20:23], v[16:19], v[24:27], v[56:59]
	v_mfma_f32_16x16x32_bf16 v[16:19], v[16:19], v[40:43], v[52:55]
	v_mfma_f32_16x16x32_bf16 v[28:31], v[12:15], v[44:47], v[20:23]
	v_mfma_f32_16x16x32_bf16 v[20:23], v[12:15], v[48:51], v[16:19]
	v_mfma_f32_16x16x32_bf16 v[12:15], v[8:11], v[24:27], v[56:59]
	s_nop 5
	v_exp_f32_e32 v28, v28
	v_exp_f32_e32 v29, v29
	v_exp_f32_e32 v30, v30
	v_mfma_f32_16x16x32_bf16 v[8:11], v[8:11], v[40:43], v[52:55]
	v_exp_f32_e32 v31, v31
	v_pk_add_f32 v[28:29], v[28:29], 1.0 op_sel_hi:[1,0]
	v_exp_f32_e32 v20, v20
	v_mfma_f32_16x16x32_bf16 v[16:19], v[4:7], v[44:47], v[12:15]
	v_rcp_f32_e32 v28, v28
	v_rcp_f32_e32 v29, v29
	v_exp_f32_e32 v21, v21
	v_mfma_f32_16x16x32_bf16 v[12:15], v[4:7], v[48:51], v[8:11]
	v_add_f32_e64 v30, v30, 1.0
	v_add_f32_e64 v31, v31, 1.0
	s_waitcnt vmcnt(0)
	v_pk_mul_f32 v[28:29], v[28:29], v[78:79] op_sel_hi:[1,0]
	v_rcp_f32_e32 v30, v30
	v_mfma_f32_16x16x32_bf16 v[4:7], v[36:39], v[24:27], v[56:59]
	v_exp_f32_e32 v28, v28
	v_exp_f32_e32 v29, v29
	v_rcp_f32_e32 v31, v31
	v_mfma_f32_16x16x32_bf16 v[24:27], v[36:39], v[40:43], v[52:55]
	v_exp_f32_e32 v16, v16
	v_exp_f32_e32 v17, v17
	v_pk_add_f32 v[20:21], v[20:21], 1.0 op_sel_hi:[1,0]
	v_mfma_f32_16x16x32_bf16 v[8:11], v[32:35], v[44:47], v[4:7]
	v_rcp_f32_e32 v20, v20
	v_rcp_f32_e32 v21, v21
	v_pk_mul_f32 v[30:31], v[30:31], v[78:79] op_sel_hi:[1,0]
	v_mfma_f32_16x16x32_bf16 v[4:7], v[32:35], v[48:51], v[24:27]
	v_exp_f32_e32 v34, v134
	v_exp_f32_e32 v35, v135
	v_exp_f32_e32 v30, v30
	v_exp_f32_e32 v24, v128
	v_exp_f32_e32 v25, v129
	v_exp_f32_e32 v26, v132
	v_exp_f32_e32 v27, v133
	v_pk_add_f32 v[34:35], v[34:35], 1.0 op_sel_hi:[1,0]
	v_pk_add_f32 v[24:25], v[24:25], 1.0 op_sel_hi:[1,0]
	v_rcp_f32_e32 v34, v34
	v_pk_add_f32 v[26:27], v[26:27], 1.0 op_sel_hi:[1,0]
	v_rcp_f32_e32 v24, v24
	v_rcp_f32_e32 v25, v25
	v_rcp_f32_e32 v26, v26
	v_rcp_f32_e32 v27, v27
	v_rcp_f32_e32 v35, v35
	v_pk_mul_f32 v[24:25], v[24:25], v[78:79] op_sel_hi:[1,0]
	v_exp_f32_e32 v31, v31
	v_pk_mul_f32 v[32:33], v[26:27], v[104:105]
	v_exp_f32_e32 v26, v24
	v_exp_f32_e32 v27, v25
	v_pk_mul_f32 v[36:37], v[34:35], v[102:103]
	v_exp_f32_e32 v22, v22
	v_exp_f32_e32 v23, v23
	v_pk_fma_f32 v[24:25], v[26:27], v[26:27], 1.0 op_sel_hi:[1,1,0] neg_lo:[1,0,0] neg_hi:[1,0,0] clamp
	v_pk_add_f32 v[16:17], v[16:17], 1.0 op_sel_hi:[1,0]
	v_sqrt_f32_e32 v24, v24
	v_sqrt_f32_e32 v25, v25
	v_rcp_f32_e32 v16, v16
	v_rcp_f32_e32 v17, v17
	v_pk_mul_f32 v[20:21], v[20:21], v[100:101]
	v_pk_mul_f32 v[24:25], v[32:33], v[24:25]
	v_exp_f32_e32 v32, v130
	v_exp_f32_e32 v33, v131
	v_exp_f32_e32 v18, v18
	v_exp_f32_e32 v19, v19
	v_pk_add_f32 v[22:23], v[22:23], 1.0 op_sel_hi:[1,0]
	v_pk_add_f32 v[32:33], v[32:33], 1.0 op_sel_hi:[1,0]
	v_rcp_f32_e32 v22, v22
	v_rcp_f32_e32 v32, v32
	v_rcp_f32_e32 v33, v33
	v_rcp_f32_e32 v23, v23
	v_pk_mul_f32 v[16:17], v[78:79], v[16:17] op_sel_hi:[0,1]
	v_exp_f32_e32 v8, v8
	v_pk_mul_f32 v[32:33], v[32:33], v[78:79] op_sel_hi:[1,0]
	v_exp_f32_e32 v9, v9
	v_exp_f32_e32 v34, v32
	v_exp_f32_e32 v35, v33
	v_exp_f32_e32 v16, v16
	v_exp_f32_e32 v17, v17
	v_exp_f32_e32 v12, v12
	v_pk_fma_f32 v[32:33], v[34:35], v[34:35], 1.0 op_sel_hi:[1,1,0] neg_lo:[1,0,0] neg_hi:[1,0,0] clamp
	v_exp_f32_e32 v13, v13
	v_sqrt_f32_e32 v32, v32
	v_sqrt_f32_e32 v33, v33
	v_pk_add_f32 v[18:19], v[18:19], 1.0 op_sel_hi:[1,0]
	v_pk_mul_f32 v[22:23], v[22:23], v[98:99]
	v_rcp_f32_e32 v18, v18
	v_pk_mul_f32 v[32:33], v[36:37], v[32:33]
	v_pk_fma_f32 v[36:37], v[28:29], v[28:29], 1.0 op_sel_hi:[1,1,0] neg_lo:[1,0,0] neg_hi:[1,0,0] clamp
	v_rcp_f32_e32 v19, v19
	v_sqrt_f32_e32 v36, v36
	v_sqrt_f32_e32 v37, v37
	v_pk_add_f32 v[8:9], v[8:9], 1.0 op_sel_hi:[1,0]
	v_pk_add_f32 v[12:13], v[12:13], 1.0 op_sel_hi:[1,0]
	v_rcp_f32_e32 v8, v8
	v_pk_mul_f32 v[20:21], v[20:21], v[36:37]
	v_pk_fma_f32 v[36:37], v[30:31], v[30:31], 1.0 op_sel_hi:[1,1,0] neg_lo:[1,0,0] neg_hi:[1,0,0] clamp
	v_rcp_f32_e32 v9, v9
	v_sqrt_f32_e32 v36, v36
	v_sqrt_f32_e32 v37, v37
	v_rcp_f32_e32 v12, v12
	v_rcp_f32_e32 v13, v13
	v_pk_mul_f32 v[18:19], v[78:79], v[18:19] op_sel_hi:[0,1]
	v_pk_mul_f32 v[22:23], v[22:23], v[36:37]
	v_pk_fma_f32 v[36:37], v[16:17], v[16:17], 1.0 op_sel_hi:[1,1,0] neg_lo:[1,0,0] neg_hi:[1,0,0] clamp
	v_exp_f32_e32 v18, v18
	v_sqrt_f32_e32 v36, v36
	v_sqrt_f32_e32 v37, v37
	v_exp_f32_e32 v19, v19
	v_pk_mul_f32 v[8:9], v[78:79], v[8:9] op_sel_hi:[0,1]
	v_exp_f32_e32 v38, v8
	v_exp_f32_e32 v39, v9
	v_pk_mul_f32 v[12:13], v[12:13], v[96:97]
	v_exp_f32_e32 v4, v4
	v_exp_f32_e32 v5, v5
	v_pk_mul_f32 v[12:13], v[12:13], v[36:37]
	v_pk_fma_f32 v[36:37], v[18:19], v[18:19], 1.0 op_sel_hi:[1,1,0] neg_lo:[1,0,0] neg_hi:[1,0,0] clamp
	v_pk_fma_f32 v[8:9], v[38:39], v[38:39], 1.0 op_sel_hi:[1,1,0] neg_lo:[1,0,0] neg_hi:[1,0,0] clamp
	v_sqrt_f32_e32 v36, v36
	v_sqrt_f32_e32 v37, v37
	v_pk_add_f32 v[4:5], v[4:5], 1.0 op_sel_hi:[1,0]
	v_rcp_f32_e32 v4, v4
	v_rcp_f32_e32 v5, v5
	v_sqrt_f32_e32 v8, v8
	v_sqrt_f32_e32 v9, v9
	v_pk_mul_f32 v[4:5], v[4:5], v[90:91]
	v_exp_f32_e32 v6, v6
	v_exp_f32_e32 v7, v7
	v_pk_mul_f32 v[4:5], v[4:5], v[8:9]
	v_exp_f32_e32 v8, v10
	v_exp_f32_e32 v9, v11
	v_pk_add_f32 v[6:7], v[6:7], 1.0 op_sel_hi:[1,0]
	v_exp_f32_e32 v14, v14
	v_rcp_f32_e32 v6, v6
	v_pk_add_f32 v[8:9], v[8:9], 1.0 op_sel_hi:[1,0]
	v_rcp_f32_e32 v7, v7
	v_rcp_f32_e32 v8, v8
	v_rcp_f32_e32 v9, v9
	v_exp_f32_e32 v15, v15
	v_pk_mul_f32 v[10:11], v[6:7], v[82:83]
	v_pk_mul_f32 v[8:9], v[78:79], v[8:9] op_sel_hi:[0,1]
	v_exp_f32_e32 v6, v8
	v_exp_f32_e32 v7, v9
	v_pk_add_f32 v[14:15], v[14:15], 1.0 op_sel_hi:[1,0]
	v_pk_fma_f32 v[8:9], v[6:7], v[6:7], 1.0 op_sel_hi:[1,1,0] neg_lo:[1,0,0] neg_hi:[1,0,0] clamp
	s_nop 0
	v_sqrt_f32_e32 v8, v8
	v_sqrt_f32_e32 v9, v9
	v_rcp_f32_e32 v14, v14
	v_rcp_f32_e32 v15, v15
	v_pk_mul_f32 v[8:9], v[10:11], v[8:9]
	s_nop 0
	v_fma_f32 v9, 0, v7, v9
	v_pk_mul_f32 v[14:15], v[14:15], v[92:93]
	v_fmac_f32_e32 v8, v6, v9
	v_mul_f32_e32 v6, v7, v6
	v_pk_mul_f32 v[14:15], v[14:15], v[36:37]
	v_mul_f32_e32 v36, v39, v6
	v_fma_f32 v5, v39, v8, v5
	v_fmac_f32_e32 v4, v38, v5
	v_mul_f32_e32 v37, v38, v36
	v_mul_f32_e32 v38, v19, v37
	v_fma_f32 v15, v19, v4, v15
	v_fmac_f32_e32 v14, v18, v15
	v_mul_f32_e32 v18, v18, v38
	v_mul_f32_e32 v19, v17, v18
	v_fma_f32 v13, v17, v14, v13
	v_fmac_f32_e32 v12, v16, v13
	v_mul_f32_e32 v16, v16, v19
	v_mul_f32_e32 v17, v31, v16
	v_fma_f32 v23, v31, v12, v23
	v_fmac_f32_e32 v22, v30, v23
	v_mul_f32_e32 v30, v30, v17
	v_mul_f32_e32 v31, v29, v30
	v_fma_f32 v21, v29, v22, v21
	v_fmac_f32_e32 v20, v28, v21
	v_mul_f32_e32 v28, v28, v31
	v_mul_f32_e32 v29, v35, v28
	v_fma_f32 v33, v35, v20, v33
	v_fmac_f32_e32 v32, v34, v33
	v_mul_f32_e32 v34, v34, v29
	v_mul_f32_e32 v35, v27, v34
	v_fma_f32 v25, v27, v32, v25
	v_fmac_f32_e32 v24, v26, v25
	v_mul_f32_e32 v3, v26, v35
	ds_bpermute_b32 v40, v114, v3
	ds_bpermute_b32 v26, v114, v24
	ds_bpermute_b32 v41, v113, v3
	ds_bpermute_b32 v27, v113, v24
	ds_bpermute_b32 v42, v112, v3
	ds_bpermute_b32 v39, v112, v24
	ds_bpermute_b32 v43, v111, v3
	ds_bpermute_b32 v11, v111, v24
	s_and_saveexec_b64 s[34:35], s[40:41]
	s_cbranch_execz .LBB0_506
	s_waitcnt lgkmcnt(6)
	v_fmac_f32_e32 v26, 0, v40
	s_waitcnt lgkmcnt(5)
	v_mul_f32_e32 v10, v40, v41
	s_waitcnt lgkmcnt(4)
	v_fmac_f32_e32 v27, v26, v41
	s_waitcnt lgkmcnt(3)
	v_mul_f32_e32 v10, v10, v42
	s_waitcnt lgkmcnt(2)
	v_fmac_f32_e32 v39, v27, v42
	v_add_co_u32_e32 v26, vcc, 0x1000, v94
	s_waitcnt lgkmcnt(1)
	v_mul_f32_e32 v10, v10, v43
	s_waitcnt lgkmcnt(0)
	v_fmac_f32_e32 v11, v39, v43
	v_addc_co_u32_e32 v27, vcc, 0, v95, vcc
	global_store_dwordx2 v[26:27], v[10:11], off sc1
	s_branch .LBB0_506
